# lever 7 (instruction selection): diff attention row-max exchange across lane halves by v_permlane32_swap on the VALU instead of a ds_bpermute LDS round trip
# speedup vs baseline: 1.0055x; 1.0038x over previous
.LBB0_565:
	v_max_f32_e32 v160, v145, v145
	v_max_f32_e32 v161, v144, v144
	v_max_f32_e32 v160, v161, v160
	v_max3_f32 v160, v160, v146, v147
	v_max3_f32 v160, v160, v148, v149
	v_max3_f32 v160, v160, v150, v151
	v_max3_f32 v160, v160, v152, v153
	v_max3_f32 v160, v160, v154, v155
	v_max3_f32 v160, v160, v156, v157
	v_max3_f32 v160, v160, v158, v159
	v_fmamk_f32 v161, v160, 0x3e38aa3b, v251
	v_cndmask_b32_e64 v160, v160, v161, s[10:11]
	v_mov_b32_e32 v161, v160
	s_waitcnt lgkmcnt(0)
	s_nop 0
	v_permlane32_swap_b32_e32 v161, v160
	v_max_f32_e32 v161, v161, v161
	v_max_f32_e32 v160, v160, v161
	v_add_f32_e32 v161, 0x41000000, v250
	v_cmp_gt_f32_e32 vcc, v160, v161
	s_cbranch_vccz .LBB0_567
	v_max_f32_e32 v160, v160, v160
	v_max_f32_e32 v161, v250, v250
	v_max_f32_e32 v161, v161, v160
	v_sub_f32_e32 v160, v250, v161
	v_exp_f32_e32 v160, v160
	v_mov_b32_e32 v250, v161
	v_mul_f32_e32 v209, v209, v160
	v_pk_mul_f32 v[126:127], v[126:127], v[160:161] op_sel_hi:[1,0]
	v_pk_mul_f32 v[124:125], v[124:125], v[160:161] op_sel_hi:[1,0]
	v_pk_mul_f32 v[122:123], v[122:123], v[160:161] op_sel_hi:[1,0]
	v_pk_mul_f32 v[120:121], v[120:121], v[160:161] op_sel_hi:[1,0]
	v_pk_mul_f32 v[118:119], v[118:119], v[160:161] op_sel_hi:[1,0]
	v_pk_mul_f32 v[116:117], v[116:117], v[160:161] op_sel_hi:[1,0]
	v_pk_mul_f32 v[114:115], v[114:115], v[160:161] op_sel_hi:[1,0]
	v_pk_mul_f32 v[112:113], v[112:113], v[160:161] op_sel_hi:[1,0]
	v_pk_mul_f32 v[78:79], v[78:79], v[160:161] op_sel_hi:[1,0]
	v_pk_mul_f32 v[76:77], v[76:77], v[160:161] op_sel_hi:[1,0]
	v_pk_mul_f32 v[74:75], v[74:75], v[160:161] op_sel_hi:[1,0]
	v_pk_mul_f32 v[72:73], v[72:73], v[160:161] op_sel_hi:[1,0]
	v_pk_mul_f32 v[70:71], v[70:71], v[160:161] op_sel_hi:[1,0]
	v_pk_mul_f32 v[68:69], v[68:69], v[160:161] op_sel_hi:[1,0]
	v_pk_mul_f32 v[66:67], v[66:67], v[160:161] op_sel_hi:[1,0]
	v_pk_mul_f32 v[64:65], v[64:65], v[160:161] op_sel_hi:[1,0]
	v_pk_mul_f32 v[46:47], v[46:47], v[160:161] op_sel_hi:[1,0]
	v_pk_mul_f32 v[44:45], v[44:45], v[160:161] op_sel_hi:[1,0]
	v_pk_mul_f32 v[42:43], v[42:43], v[160:161] op_sel_hi:[1,0]
	v_pk_mul_f32 v[40:41], v[40:41], v[160:161] op_sel_hi:[1,0]
	v_pk_mul_f32 v[38:39], v[38:39], v[160:161] op_sel_hi:[1,0]
	v_pk_mul_f32 v[36:37], v[36:37], v[160:161] op_sel_hi:[1,0]
	v_pk_mul_f32 v[34:35], v[34:35], v[160:161] op_sel_hi:[1,0]
	v_pk_mul_f32 v[32:33], v[32:33], v[160:161] op_sel_hi:[1,0]
	v_pk_mul_f32 v[14:15], v[14:15], v[160:161] op_sel_hi:[1,0]
	v_pk_mul_f32 v[12:13], v[12:13], v[160:161] op_sel_hi:[1,0]
	v_pk_mul_f32 v[10:11], v[10:11], v[160:161] op_sel_hi:[1,0]
	v_pk_mul_f32 v[8:9], v[8:9], v[160:161] op_sel_hi:[1,0]
	v_pk_mul_f32 v[6:7], v[6:7], v[160:161] op_sel_hi:[1,0]
	v_pk_mul_f32 v[4:5], v[4:5], v[160:161] op_sel_hi:[1,0]
	v_pk_mul_f32 v[2:3], v[2:3], v[160:161] op_sel_hi:[1,0]
	v_pk_mul_f32 v[0:1], v[0:1], v[160:161] op_sel_hi:[1,0]

.LBB0_601:
	v_max_f32_e32 v144, v129, v129
	v_max_f32_e32 v145, v128, v128
	v_max_f32_e32 v144, v145, v144
	v_max3_f32 v144, v144, v130, v131
	v_max3_f32 v144, v144, v132, v133
	v_max3_f32 v144, v144, v134, v135
	v_max3_f32 v144, v144, v136, v137
	v_max3_f32 v144, v144, v138, v139
	v_max3_f32 v144, v144, v140, v141
	v_max3_f32 v144, v144, v142, v143
	v_fmac_f32_e32 v251, 0x3e38aa3b, v144
	v_cndmask_b32_e64 v144, v144, v251, s[10:11]
	v_mov_b32_e32 v145, v144
	s_waitcnt lgkmcnt(0)
	s_nop 0
	v_permlane32_swap_b32_e32 v145, v144
	v_max_f32_e32 v145, v145, v145
	v_max_f32_e32 v144, v144, v145
	v_add_f32_e32 v145, 0x41000000, v203
	v_cmp_gt_f32_e32 vcc, v144, v145
	s_cbranch_vccz .LBB0_526
	v_max_f32_e32 v144, v144, v144
	v_max_f32_e32 v145, v203, v203
	v_max_f32_e32 v145, v145, v144
	v_sub_f32_e32 v144, v203, v145
	v_exp_f32_e32 v144, v144
	v_mov_b32_e32 v203, v145
	v_mul_f32_e32 v208, v208, v144
	v_pk_mul_f32 v[110:111], v[110:111], v[144:145] op_sel_hi:[1,0]
	v_pk_mul_f32 v[108:109], v[108:109], v[144:145] op_sel_hi:[1,0]
	v_pk_mul_f32 v[106:107], v[106:107], v[144:145] op_sel_hi:[1,0]
	v_pk_mul_f32 v[104:105], v[104:105], v[144:145] op_sel_hi:[1,0]
	v_pk_mul_f32 v[102:103], v[102:103], v[144:145] op_sel_hi:[1,0]
	v_pk_mul_f32 v[100:101], v[100:101], v[144:145] op_sel_hi:[1,0]
	v_pk_mul_f32 v[98:99], v[98:99], v[144:145] op_sel_hi:[1,0]
	v_pk_mul_f32 v[96:97], v[96:97], v[144:145] op_sel_hi:[1,0]
	v_pk_mul_f32 v[94:95], v[94:95], v[144:145] op_sel_hi:[1,0]
	v_pk_mul_f32 v[92:93], v[92:93], v[144:145] op_sel_hi:[1,0]
	v_pk_mul_f32 v[90:91], v[90:91], v[144:145] op_sel_hi:[1,0]
	v_pk_mul_f32 v[88:89], v[88:89], v[144:145] op_sel_hi:[1,0]
	v_pk_mul_f32 v[86:87], v[86:87], v[144:145] op_sel_hi:[1,0]
	v_pk_mul_f32 v[84:85], v[84:85], v[144:145] op_sel_hi:[1,0]
	v_pk_mul_f32 v[82:83], v[82:83], v[144:145] op_sel_hi:[1,0]
	v_pk_mul_f32 v[80:81], v[80:81], v[144:145] op_sel_hi:[1,0]
	v_pk_mul_f32 v[62:63], v[62:63], v[144:145] op_sel_hi:[1,0]
	v_pk_mul_f32 v[60:61], v[60:61], v[144:145] op_sel_hi:[1,0]
	v_pk_mul_f32 v[58:59], v[58:59], v[144:145] op_sel_hi:[1,0]
	v_pk_mul_f32 v[56:57], v[56:57], v[144:145] op_sel_hi:[1,0]
	v_pk_mul_f32 v[54:55], v[54:55], v[144:145] op_sel_hi:[1,0]
	v_pk_mul_f32 v[52:53], v[52:53], v[144:145] op_sel_hi:[1,0]
	v_pk_mul_f32 v[50:51], v[50:51], v[144:145] op_sel_hi:[1,0]
	v_pk_mul_f32 v[48:49], v[48:49], v[144:145] op_sel_hi:[1,0]
	v_pk_mul_f32 v[30:31], v[30:31], v[144:145] op_sel_hi:[1,0]
	v_pk_mul_f32 v[28:29], v[28:29], v[144:145] op_sel_hi:[1,0]
	v_pk_mul_f32 v[26:27], v[26:27], v[144:145] op_sel_hi:[1,0]
	v_pk_mul_f32 v[24:25], v[24:25], v[144:145] op_sel_hi:[1,0]
	v_pk_mul_f32 v[22:23], v[22:23], v[144:145] op_sel_hi:[1,0]
	v_pk_mul_f32 v[20:21], v[20:21], v[144:145] op_sel_hi:[1,0]
	v_pk_mul_f32 v[18:19], v[18:19], v[144:145] op_sel_hi:[1,0]
	v_pk_mul_f32 v[16:17], v[16:17], v[144:145] op_sel_hi:[1,0]
	s_branch .LBB0_526
